# grid-barrier seams: the acquire-side L1 invalidate (buffer_inv sc1) is issued by wave 1 right after the workgroup has drained and arrived (no wave of the CU issues cached loads until the closing barri
# speedup vs baseline: 1.0195x; 1.0055x over previous
; __device__ __forceinline__ unsigned xb_ld(unsigned* p)              { return __hip_atomic_load(p, __ATOMIC_RELAXED, __HIP_MEMORY_SCOPE_AGENT); }
; __device__ __forceinline__ void xcd_barrier_complete(unsigned* bar, unsigned x, unsigned& nloc, unsigned& nx) {
;     const unsigned G = gridDim.x * gridDim.y * gridDim.z;
;     unsigned sum, cnt, mine, sp = 0u;
;     for (;;) {
;         sum = 0u; cnt = 0u; mine = 0u;
; #pragma unroll
;         for (unsigned j = 0; j < 16; ++j) { const unsigned c = xb_ld(&bar[XB_XCNT(j)]); sum += c; cnt += (c > 0u) ? 1u : 0u; mine = (j == x) ? c : mine; }
; __device__ __forceinline__ void xcd_barrier(const XcdBarrier& b) {
;     asm volatile("s_waitcnt vmcnt(0)" ::: "memory");
;     __syncthreads();
;     if (threadIdx.x == 0) {
;         unsigned* bar = b.bar;
;         __builtin_amdgcn_s_waitcnt(0);
;         unsigned nloc = b.st[0], nx = b.st[1];
;         if (nloc == 0u) { xcd_barrier_complete(bar, b.x, nloc, nx); b.st[0] = nloc; b.st[1] = nx; }
.LBB0_75:
	s_mov_b64 s[2:3], s[92:93]
	s_getreg_b32 s4, hwreg(HW_REG_XCC_ID, 0, 4)
	s_waitcnt vmcnt(0)
	s_barrier
	v_readfirstlane_b32 s99, v145
	s_nop 3
	s_lshr_b32 s99, s99, 6
	s_cmp_eq_u32 s99, 1
	s_cbranch_scc0 .Lseam0_noinv
	buffer_inv sc1
.Lseam0_noinv:
	s_and_saveexec_b64 s[0:1], s[64:65]
	s_cbranch_execz .LBB0_127
	v_mov_b32_e32 v0, 0x20160
	s_load_dwordx4 s[8:11], s[2:3], 0xc8
	s_waitcnt vmcnt(0) expcnt(0) lgkmcnt(0)
	ds_read_b32 v4, v0
	v_mov_b32_e32 v0, 0x20164
	ds_read_b32 v0, v0
	s_add_u32 s2, s8, s10
	s_addc_u32 s3, s9, s11
	s_waitcnt lgkmcnt(1)
	v_cmp_ne_u32_e32 vcc, 0, v4
	s_and_b32 s33, s4, 15
	s_cbranch_vccnz .LBB0_91
	s_add_u32 s4, s2, 0x11500200
	s_addc_u32 s5, s3, 0
	s_add_u32 s6, s2, 0x11500400
	s_addc_u32 s7, s3, 0
	s_add_u32 s8, s2, 0x11500500
	s_addc_u32 s9, s3, 0
	s_add_u32 s10, s2, 0x11500600
	s_addc_u32 s11, s3, 0
	s_add_u32 s12, s2, 0x11500700
	s_addc_u32 s13, s3, 0
	s_add_u32 s14, s2, 0x11500800
	s_addc_u32 s15, s3, 0
	s_add_u32 s16, s2, 0x11500900
	s_addc_u32 s17, s3, 0
	s_add_u32 s18, s2, 0x11500a00
	s_addc_u32 s19, s3, 0
	s_add_u32 s20, s2, 0x11500b00
	s_addc_u32 s21, s3, 0
	s_add_u32 s22, s2, 0x11500c00
	s_addc_u32 s23, s3, 0
	s_add_u32 s24, s2, 0x11500d00
	s_addc_u32 s25, s3, 0
	s_add_u32 s26, s2, 0x11500e00
	s_addc_u32 s27, s3, 0
	s_add_u32 s28, s2, 0x11500f00
	s_addc_u32 s29, s3, 0
	s_add_u32 s30, s2, 0x11501000
	s_addc_u32 s31, s3, 0
	s_add_u32 s34, s2, 0x11501100
	s_addc_u32 s35, s3, 0
	s_add_u32 s36, s2, 0x11501200
	s_addc_u32 s37, s3, 0
	s_mul_i32 s49, s63, s46
	s_add_u32 s38, s2, 0x11501300
	s_mul_i32 s49, s49, s62
	s_addc_u32 s39, s3, 0
	s_mov_b32 s50, 1
	v_mov_b32_e32 v18, 0
	s_branch .LBB0_79

; __device__ __forceinline__ unsigned xb_ld(unsigned* p)              { return __hip_atomic_load(p, __ATOMIC_RELAXED, __HIP_MEMORY_SCOPE_AGENT); }
; #define XB_SPIN(cond, bar) do { unsigned _sp = 0; while (cond) { __builtin_amdgcn_s_sleep(1); \
;     if ((++_sp & 255u) == 0u) { if (xb_ld(&(bar)[XB_TMO])) break; if (_sp > XB_SPIN_CAP) { atomicAdd(&(bar)[XB_TMO], 1u); break; } } } } while (0)
; __device__ __forceinline__ void xcd_barrier(const XcdBarrier& b) {
;     ...
;         } else {
;             XB_SPIN(xb_ld(&bar[XB_XGEN(b.x)]) == gen, bar);
;             __builtin_amdgcn_fence(__ATOMIC_ACQUIRE, "agent");
;             asm volatile("s_waitcnt vmcnt(0)" ::: "memory");
.LBB0_106:
	s_or_b64 exec, exec, s[8:9]
	s_waitcnt vmcnt(0)
	s_waitcnt vmcnt(0)

; __device__ __forceinline__ unsigned xb_ld(unsigned* p)              { return __hip_atomic_load(p, __ATOMIC_RELAXED, __HIP_MEMORY_SCOPE_AGENT); }
; __device__ __forceinline__ unsigned xb_add(unsigned* p, unsigned v) { return __hip_atomic_fetch_add(p, v, __ATOMIC_RELAXED, __HIP_MEMORY_SCOPE_AGENT); }
; #define XB_SPIN(cond, bar) do { unsigned _sp = 0; while (cond) { __builtin_amdgcn_s_sleep(1); \
;     if ((++_sp & 255u) == 0u) { if (xb_ld(&(bar)[XB_TMO])) break; if (_sp > XB_SPIN_CAP) { atomicAdd(&(bar)[XB_TMO], 1u); break; } } } } while (0)
; __device__ __forceinline__ void xcd_barrier(const XcdBarrier& b) {
;     ...
;             if (og + 1u == (tg + 1u) * nx) xb_add(&bar[XB_TOPGEN], 1u);
;             else XB_SPIN(xb_ld(&bar[XB_TOPGEN]) == tg, bar);
;             __builtin_amdgcn_fence(__ATOMIC_ACQUIRE, "agent");
;             xb_add(&bar[XB_XGEN(b.x)], 1u);
;             asm volatile("s_waitcnt vmcnt(0)" ::: "memory");
.LBB0_124:
	s_or_b64 exec, exec, s[2:3]
	s_mov_b64 s[2:3], exec
	v_mbcnt_lo_u32_b32 v0, s2, 0
	v_mbcnt_hi_u32_b32 v0, s3, v0
	v_cmp_eq_u32_e32 vcc, 0, v0
	s_waitcnt vmcnt(0)
	s_and_saveexec_b64 s[6:7], vcc
	s_cbranch_execz .LBB0_126
	s_bcnt1_i32_b64 s2, s[2:3]
	v_mov_b32_e32 v0, 0x2000
	v_mov_b32_e32 v1, s2
	global_atomic_add v0, v1, s[4:5] offset:1024

;     __host__ __device__ bool next(int i, Unit& u) const {
;         const long L = (long)i * G + c; if (L >= nwg) return false;
;         int wgid = (int)L; { const int q = nwg / NXCD, r = nwg % NXCD, xcd = wgid % NXCD, off = wgid / NXCD; wgid = (xcd < r ? xcd * (q + 1) : r * (q + 1) + (xcd - r) * q) + off; }
;         const int nig = WGM * nN, gid = wgid / nig, fm = gid * WGM, gsz = (nM - fm) < WGM ? (nM - fm) : WGM;
;         u.pm = fm + ((wgid % nig) % gsz); u.pn = (wgid % nig) / gsz; return true;
;     }
; __device__ __forceinline__ void xcd_barrier(const XcdBarrier& b) {
;     ...
;     __syncthreads();
.LBB0_127:
	v_writelane_b32 v252, s90, 8
	s_nop 1
	v_writelane_b32 v252, s91, 9
	v_writelane_b32 v252, s88, 10
	s_nop 1
	v_writelane_b32 v252, s89, 11
	s_or_b64 exec, exec, s[0:1]
	s_ashr_i32 s68, s62, 31
	s_ashr_i32 s97, s96, 31
	s_cmpk_lt_i32 s96, 0xb00
	s_cselect_b64 s[72:73], -1, 0
	s_lshr_b32 s0, s97, 29
	s_add_i32 s0, s96, s0
	s_ashr_i32 s3, s0, 3
	s_and_b32 s0, s0, -8
	s_sub_i32 s4, s96, s0
	s_cmpk_lt_i32 s96, 0x200
	s_cselect_b64 s[74:75], -1, 0
	s_lshl_b32 s0, s4, 6
	s_cmpk_lt_i32 s96, 0x400
	s_cselect_b64 s[6:7], -1, 0
	s_lshl_b32 s1, s4, 7
	v_writelane_b32 v252, s6, 12
	s_cmpk_lt_i32 s96, 0x100
	s_movk_i32 s71, 0x161
	v_writelane_b32 v252, s7, 13
	s_cselect_b64 s[6:7], -1, 0
	s_lshl_b32 s10, s48, 4
	s_cmpk_gt_u32 s47, 0x7f
	s_cselect_b64 s[80:81], -1, 0
	s_cmpk_gt_u32 s47, 0xff
	s_cselect_b64 s[82:83], -1, 0
	s_cmpk_gt_u32 s47, 0x17f
	v_writelane_b32 v252, s6, 14
	s_cselect_b64 s[84:85], -1, 0
	s_cmpk_lt_i32 s96, 0x300
	v_writelane_b32 v252, s7, 15
	s_cselect_b64 s[6:7], -1, 0
	v_writelane_b32 v252, s6, 16
	s_lshl_b32 s2, s48, 14
	s_lshl_b32 s11, s48, 3
	v_writelane_b32 v252, s7, 17
	v_writelane_b32 v252, s2, 18
	s_cmp_lt_i32 s4, 0
	s_mul_i32 s2, s63, s62
	s_waitcnt lgkmcnt(0)
	v_or_b32_e32 v0, v3, v2
	s_movk_i32 s5, 0x3ff
	s_mul_i32 s63, s2, s46
	s_mul_i32 s2, s4, 0x41
	s_cselect_b32 s6, s71, 0x160
	v_and_or_b32 v0, v0, s5, v145
	s_mul_i32 s5, s4, 0x81
	s_mul_i32 s6, s4, s6
	s_cselect_b32 s2, s2, s0
	s_movk_i32 s0, 0x61
	s_cselect_b32 s5, s5, s1
	s_cselect_b32 s7, s0, 0x60
	s_add_i32 s6, s6, s3
	s_mul_hi_i32 s0, s6, 0x2e8ba2e9
	s_lshr_b32 s1, s0, 31
	s_ashr_i32 s0, s0, 5
	s_add_i32 s0, s0, s1
	s_mul_i32 s1, s0, 0xb0
	s_sub_i32 s1, s6, s1
	s_lshl_b32 s8, s0, 3
	s_bfe_u32 s0, s1, 0x3001c
	s_add_i32 s6, s1, s0
	s_sext_i32_i16 s9, s6
	s_and_b32 s6, s6, 0xfff8
	s_sub_i32 s1, s1, s6
	s_sext_i32_i16 s1, s1
	s_add_i32 s8, s8, s1
	s_ashr_i32 s1, s9, 3
	v_writelane_b32 v252, s1, 19
	s_mov_b32 s6, s8
	s_lshr_b32 s0, s9, 3
	s_ashr_i32 s9, s8, 31
	v_writelane_b32 v252, s6, 20
	s_lshl_b64 s[8:9], s[8:9], 19
	s_bfe_i64 s[0:1], s[0:1], 0x100000
	v_writelane_b32 v252, s7, 21
	v_writelane_b32 v252, s8, 22
	s_lshl_b64 s[0:1], s[0:1], 19
	s_mov_b32 s69, s62
	v_writelane_b32 v252, s9, 23
	v_writelane_b32 v252, s0, 24
	s_lshl_b32 s47, s62, 7
	v_writelane_b32 v253, s69, 0
	v_writelane_b32 v252, s1, 25
	s_add_i32 s0, s2, s3
	s_ashr_i32 s1, s0, 31
	s_lshr_b32 s1, s1, 27
	s_add_i32 s1, s0, s1
	s_ashr_i32 s2, s1, 5
	s_and_b32 s1, s1, 0xffe0
	s_sub_i32 s1, s0, s1
	s_bfe_i32 s0, s1, 0x80000
	s_bfe_u32 s0, s0, 0x3000c
	s_add_i32 s6, s1, s0
	s_bfe_i32 s0, s6, 0x80000
	s_and_b32 s6, s6, 0xf8
	s_sub_i32 s1, s1, s6
	s_lshl_b32 s2, s2, 3
	s_sext_i32_i16 s8, s0
	s_sext_i32_i8 s1, s1
	s_add_i32 s12, s2, s1
	s_ashr_i32 s1, s8, 3
	v_writelane_b32 v252, s1, 26
	s_add_i32 s1, s5, s3
	s_ashr_i32 s2, s1, 31
	s_lshr_b32 s2, s2, 26
	s_add_i32 s2, s1, s2
	s_ashr_i32 s5, s2, 6
	s_and_b32 s2, s2, 0xffc0
	s_sub_i32 s1, s1, s2
	s_bfe_i32 s2, s1, 0x80000
	s_bfe_u32 s2, s2, 0x3000c
	s_add_i32 s6, s1, s2
	s_bfe_i32 s2, s6, 0x80000
	s_and_b32 s6, s6, 0xf8
	s_sub_i32 s1, s1, s6
	s_lshr_b32 s0, s8, 3
	s_lshl_b32 s5, s5, 3
	s_sext_i32_i16 s8, s2
	s_sext_i32_i8 s1, s1
	s_add_i32 s14, s5, s1
	s_ashr_i32 s1, s8, 3
	v_writelane_b32 v252, s1, 27
	s_mul_i32 s1, s4, s7
	s_add_i32 s1, s1, s3
	s_mul_hi_i32 s3, s1, 0x2aaaaaab
	s_lshr_b32 s4, s3, 31
	s_ashr_i32 s3, s3, 3
	s_add_i32 s3, s3, s4
	s_lshl_b32 s5, s3, 3
	s_mul_i32 s3, s3, 48
	s_sub_i32 s1, s1, s3
	s_bfe_i32 s3, s1, 0x80000
	s_bfe_u32 s3, s3, 0x3000c
	s_add_i32 s3, s1, s3
	s_bfe_i32 s4, s3, 0x80000
	s_and_b32 s3, s3, 0xf8
	s_sub_i32 s1, s1, s3
	s_sext_i32_i16 s6, s4
	s_sext_i32_i8 s1, s1
	s_lshr_b32 s2, s8, 3
	s_add_i32 s8, s5, s1
	s_ashr_i32 s1, s6, 3
	s_lshr_b32 s4, s6, 3
	v_writelane_b32 v252, s1, 28
	s_mov_b32 s6, s8
	s_ashr_i32 s9, s8, 31
	v_writelane_b32 v252, s6, 29
	s_bfe_i64 s[4:5], s[4:5], 0x100000
	s_lshl_b64 s[4:5], s[4:5], 19
	v_writelane_b32 v252, s7, 30
	s_lshl_b64 s[6:7], s[8:9], 19
	v_writelane_b32 v252, s6, 31
	s_ashr_i32 s15, s14, 31
	s_bfe_i64 s[2:3], s[2:3], 0x100000
	v_writelane_b32 v252, s7, 32
	v_writelane_b32 v252, s4, 33
	s_lshl_b64 s[2:3], s[2:3], 19
	s_ashr_i32 s13, s12, 31
	v_writelane_b32 v252, s5, 34
	s_mov_b32 s4, s14
	v_writelane_b32 v252, s4, 35
	s_bfe_i64 s[0:1], s[0:1], 0x100000
	s_lshl_b64 s[0:1], s[0:1], 19
	v_writelane_b32 v252, s5, 36
	s_lshl_b64 s[4:5], s[14:15], 19
	v_writelane_b32 v252, s4, 37
	v_writelane_b32 v253, s72, 1
	v_cmp_eq_u32_e64 s[90:91], 0, v0
	v_writelane_b32 v252, s5, 38
	v_writelane_b32 v252, s2, 39
	v_writelane_b32 v253, s73, 2
	v_writelane_b32 v253, s74, 3
	v_writelane_b32 v252, s3, 40
	s_mov_b32 s2, s12
	v_writelane_b32 v252, s2, 41
	v_writelane_b32 v253, s75, 4
	v_writelane_b32 v253, s80, 5
	v_writelane_b32 v252, s3, 42
	s_lshl_b64 s[2:3], s[12:13], 19
	v_writelane_b32 v252, s2, 43
	v_writelane_b32 v253, s81, 6
	v_writelane_b32 v253, s82, 7
	v_writelane_b32 v252, s3, 44
	v_writelane_b32 v252, s0, 45
	v_writelane_b32 v253, s83, 8
	v_writelane_b32 v253, s84, 9
	v_writelane_b32 v252, s1, 46
	s_lshl_b32 s0, s96, 7
	v_writelane_b32 v252, s10, 47
	s_add_i32 s1, s0, s10
	v_writelane_b32 v252, s1, 48
	s_or_b32 s1, s0, 0x60
	v_writelane_b32 v252, s1, 49
	s_or_b32 s1, s0, 64
	v_writelane_b32 v252, s1, 50
	v_writelane_b32 v252, s0, 51
	s_or_b32 s0, s0, 32
	v_writelane_b32 v252, s0, 52
	s_lshl_b32 s0, s96, 6
	v_writelane_b32 v252, s11, 53
	s_add_i32 s0, s0, s11
	v_writelane_b32 v252, s0, 54
	s_lshl_b32 s0, s62, 6
	v_writelane_b32 v252, s0, 55
	v_writelane_b32 v252, s47, 56
	v_writelane_b32 v252, s92, 57
	v_writelane_b32 v253, s85, 10
	v_writelane_b32 v253, s90, 11
	v_writelane_b32 v252, s93, 58
	v_writelane_b32 v252, s96, 59
	v_writelane_b32 v253, s91, 12
	s_movk_i32 s70, 0xb00
	v_writelane_b32 v252, s97, 60
	v_writelane_b32 v252, s66, 61
	s_mov_b32 s89, 0
	s_mov_b32 s25, 1
	v_writelane_b32 v252, s67, 62
	s_mov_b64 s[26:27], 0xb00
	v_mov_b32_e32 v193, 0x358637bd
	v_mov_b32_e32 v146, 0
	s_mov_b64 s[94:95], 0x80
	s_movk_i32 s59, 0x1600
	v_mov_b32_e32 v194, 0x20160
	v_mov_b32_e32 v195, 0x20164
	v_mov_b32_e32 v196, 0x1000
	v_mov_b32_e32 v197, 0x2000
	v_mov_b32_e32 v199, 1
	s_mov_b64 s[30:31], 0x200
	v_mbcnt_hi_u32_b32 v192, -1, v40
	s_mov_b32 s87, 0x40000
	s_mov_b64 s[34:35], 0x8000
	v_mov_b32_e32 v200, 0x160
	v_mov_b32_e32 v201, 0x161
	v_mov_b32_e32 v202, 0x20400
	v_mov_b32_e32 v203, 0x20c00
	v_mov_b32_e32 v204, 0x21400
	v_mov_b32_e32 v205, 0x21c00
	v_mov_b32_e32 v206, 0x22400
	v_mov_b32_e32 v207, 0x22c00
	v_mov_b64_e32 v[148:149], 0xaff
	v_mov_b64_e32 v[150:151], 0x200
	v_mov_b64_e32 v[152:153], 0x1ff
	v_mov_b64_e32 v[154:155], 0x400
	v_mov_b64_e32 v[156:157], 0x3ff
	v_mov_b32_e32 v198, 0x60
	v_mov_b64_e32 v[158:159], 0x300
	v_mov_b64_e32 v[160:161], 0x2ff
	s_mov_b32 s76, 0
	v_writelane_b32 v252, s68, 63
	v_writelane_b32 v253, s63, 13
	s_waitcnt vmcnt(0)
	s_barrier
	s_cmp_lt_u32 s25, 16
	s_cbranch_scc0 .LBB0_459
	s_branch .LBB0_419

; __device__ __forceinline__ unsigned xb_ld(unsigned* p)              { return __hip_atomic_load(p, __ATOMIC_RELAXED, __HIP_MEMORY_SCOPE_AGENT); }
; __device__ __forceinline__ unsigned xb_add(unsigned* p, unsigned v) { return __hip_atomic_fetch_add(p, v, __ATOMIC_RELAXED, __HIP_MEMORY_SCOPE_AGENT); }
; #define XB_SPIN(cond, bar) do { unsigned _sp = 0; while (cond) { __builtin_amdgcn_s_sleep(1); \
;     if ((++_sp & 255u) == 0u) { if (xb_ld(&(bar)[XB_TMO])) break; if (_sp > XB_SPIN_CAP) { atomicAdd(&(bar)[XB_TMO], 1u); break; } } } } while (0)
; __device__ __forceinline__ void xcd_barrier(const XcdBarrier& b) {
;     ...
;             if (og + 1u == (tg + 1u) * nx) xb_add(&bar[XB_TOPGEN], 1u);
;             else XB_SPIN(xb_ld(&bar[XB_TOPGEN]) == tg, bar);
;             __builtin_amdgcn_fence(__ATOMIC_ACQUIRE, "agent");
;             xb_add(&bar[XB_XGEN(b.x)], 1u);
;             asm volatile("s_waitcnt vmcnt(0)" ::: "memory");
.LBB0_132:
	s_or_b64 exec, exec, s[2:3]
	s_mov_b64 s[2:3], exec
	v_mbcnt_lo_u32_b32 v0, s2, 0
	v_mbcnt_hi_u32_b32 v0, s3, v0
	v_cmp_eq_u32_e32 vcc, 0, v0
	s_waitcnt vmcnt(0)
	s_and_saveexec_b64 s[6:7], vcc
	s_cbranch_execz .LBB0_134
	s_bcnt1_i32_b64 s2, s[2:3]
	v_mov_b32_e32 v0, s2
	global_atomic_add v197, v0, s[4:5] offset:1024

; __device__ __forceinline__ void xcd_barrier(const XcdBarrier& b) {
;     ...
;             asm volatile("s_waitcnt vmcnt(0)" ::: "memory");
;         }
;     }
;     __syncthreads();
.LBB0_135:
	s_or_b64 exec, exec, s[0:1]
	s_waitcnt vmcnt(0) lgkmcnt(0)
	s_barrier

; __device__ __forceinline__ void xcd_barrier(const XcdBarrier& b) {
;     asm volatile("s_waitcnt vmcnt(0)" ::: "memory");
;     __syncthreads();
;     if (threadIdx.x == 0) {
;         unsigned* bar = b.bar;
;         __builtin_amdgcn_s_waitcnt(0);
;         unsigned nloc = b.st[0], nx = b.st[1];
;         if (nloc == 0u) { xcd_barrier_complete(bar, b.x, nloc, nx); b.st[0] = nloc; b.st[1] = nx; }
.LBB0_260:
	s_mov_b64 s[2:3], s[92:93]
	s_getreg_b32 s4, hwreg(HW_REG_XCC_ID, 0, 4)
	s_waitcnt vmcnt(0)
	s_waitcnt vmcnt(0) lgkmcnt(0)
	s_barrier
	v_readfirstlane_b32 s99, v145
	s_nop 3
	s_lshr_b32 s99, s99, 6
	s_cmp_eq_u32 s99, 1
	s_cbranch_scc0 .Lseam1_noinv
	buffer_inv sc1
.Lseam1_noinv:
	s_and_saveexec_b64 s[0:1], s[64:65]
	s_cbranch_execz .LBB0_312
	s_load_dwordx4 s[8:11], s[2:3], 0xc8
	s_waitcnt vmcnt(0) expcnt(0) lgkmcnt(0)
	ds_read_b32 v2, v194
	ds_read_b32 v0, v195
	s_add_u32 s2, s8, s10
	s_waitcnt lgkmcnt(1)
	v_cmp_ne_u32_e32 vcc, 0, v2
	s_addc_u32 s3, s9, s11
	s_and_b32 s33, s4, 15
	s_cbranch_vccnz .LBB0_276
	s_add_u32 s4, s2, 0x11500200
	s_addc_u32 s5, s3, 0
	s_add_u32 s6, s2, 0x11500400
	s_addc_u32 s7, s3, 0
	s_add_u32 s8, s2, 0x11500500
	s_addc_u32 s9, s3, 0
	s_add_u32 s10, s2, 0x11500600
	s_addc_u32 s11, s3, 0
	s_add_u32 s12, s2, 0x11500700
	s_addc_u32 s13, s3, 0
	s_add_u32 s14, s2, 0x11500800
	s_addc_u32 s15, s3, 0
	s_add_u32 s16, s2, 0x11500900
	s_addc_u32 s17, s3, 0
	s_add_u32 s18, s2, 0x11500a00
	s_addc_u32 s19, s3, 0
	s_add_u32 s20, s2, 0x11500b00
	s_addc_u32 s21, s3, 0
	s_add_u32 s22, s2, 0x11500c00
	s_addc_u32 s23, s3, 0
	s_add_u32 s24, s2, 0x11500d00
	s_mov_b32 s48, s25
	s_addc_u32 s25, s3, 0
	s_add_u32 s26, s2, 0x11500e00
	s_addc_u32 s27, s3, 0
	s_add_u32 s28, s2, 0x11500f00
	s_addc_u32 s29, s3, 0
	s_add_u32 s30, s2, 0x11501000
	s_addc_u32 s31, s3, 0
	s_add_u32 s34, s2, 0x11501100
	s_addc_u32 s35, s3, 0
	s_add_u32 s36, s2, 0x11501200
	s_addc_u32 s37, s3, 0
	s_add_u32 s38, s2, 0x11501300
	s_addc_u32 s39, s3, 0
	s_mov_b32 s46, 1
	s_branch .LBB0_264

; __device__ __forceinline__ void xcd_barrier(const XcdBarrier& b) {
;     asm volatile("s_waitcnt vmcnt(0)" ::: "memory");
;     __syncthreads();
;     if (threadIdx.x == 0) {
.LBB0_472:
	s_mov_b64 s[2:3], s[92:93]
	s_getreg_b32 s4, hwreg(HW_REG_XCC_ID, 0, 4)
	s_waitcnt vmcnt(0)
	s_waitcnt vmcnt(0)
	s_barrier
	v_readfirstlane_b32 s99, v145
	s_nop 3
	s_lshr_b32 s99, s99, 6
	s_cmp_eq_u32 s99, 1
	s_cbranch_scc0 .Lseam3_noinv
	buffer_inv sc1

; __device__ __forceinline__ unsigned xb_ld(unsigned* p)              { return __hip_atomic_load(p, __ATOMIC_RELAXED, __HIP_MEMORY_SCOPE_AGENT); }
; __device__ __forceinline__ void xcd_barrier_complete(unsigned* bar, unsigned x, unsigned& nloc, unsigned& nx) {
;     const unsigned G = gridDim.x * gridDim.y * gridDim.z;
;     unsigned sum, cnt, mine, sp = 0u;
;     for (;;) {
;         sum = 0u; cnt = 0u; mine = 0u;
; #pragma unroll
;         for (unsigned j = 0; j < 16; ++j) { const unsigned c = xb_ld(&bar[XB_XCNT(j)]); sum += c; cnt += (c > 0u) ? 1u : 0u; mine = (j == x) ? c : mine; }
; __device__ __forceinline__ void xcd_barrier(const XcdBarrier& b) {
;     ...
;     if (threadIdx.x == 0) {
;         unsigned* bar = b.bar;
;         __builtin_amdgcn_s_waitcnt(0);
;         unsigned nloc = b.st[0], nx = b.st[1];
;         if (nloc == 0u) { xcd_barrier_complete(bar, b.x, nloc, nx); b.st[0] = nloc; b.st[1] = nx; }
.Lseam5_noinv:
	s_and_saveexec_b64 s[0:1], s[64:65]
	s_cbranch_execz .LBB0_939
	s_load_dwordx4 s[8:11], s[2:3], 0xc8
	s_waitcnt vmcnt(0) expcnt(0) lgkmcnt(0)
	ds_read_b32 v2, v194
	ds_read_b32 v0, v195
	s_add_u32 s2, s8, s10
	s_waitcnt lgkmcnt(1)
	v_cmp_ne_u32_e32 vcc, 0, v2
	s_addc_u32 s3, s9, s11
	s_and_b32 s33, s4, 15
	s_cbranch_vccnz .LBB0_869
	s_add_u32 s4, s2, 0x11500200
	s_addc_u32 s5, s3, 0
	s_add_u32 s6, s2, 0x11500400
	s_addc_u32 s7, s3, 0
	s_add_u32 s8, s2, 0x11500500
	s_addc_u32 s9, s3, 0
	s_add_u32 s10, s2, 0x11500600
	s_addc_u32 s11, s3, 0
	s_add_u32 s12, s2, 0x11500700
	s_addc_u32 s13, s3, 0
	s_add_u32 s14, s2, 0x11500800
	s_addc_u32 s15, s3, 0
	s_add_u32 s16, s2, 0x11500900
	s_addc_u32 s17, s3, 0
	s_add_u32 s18, s2, 0x11500a00
	s_addc_u32 s19, s3, 0
	s_add_u32 s20, s2, 0x11500b00
	s_addc_u32 s21, s3, 0
	s_add_u32 s22, s2, 0x11500c00
	s_addc_u32 s23, s3, 0
	s_add_u32 s24, s2, 0x11500d00
	s_mov_b32 s48, s25
	s_addc_u32 s25, s3, 0
	s_add_u32 s26, s2, 0x11500e00
	s_addc_u32 s27, s3, 0
	s_add_u32 s28, s2, 0x11500f00
	s_addc_u32 s29, s3, 0
	s_add_u32 s30, s2, 0x11501000
	s_addc_u32 s31, s3, 0
	s_add_u32 s34, s2, 0x11501100
	s_addc_u32 s35, s3, 0
	s_add_u32 s36, s2, 0x11501200
	s_addc_u32 s37, s3, 0
	s_add_u32 s38, s2, 0x11501300
	s_addc_u32 s39, s3, 0
	s_mov_b32 s47, 1
	s_branch .LBB0_832
